# v50 plus: non-leader workgroups poll the cross-XCD release word directly (one hop fewer per grid barrier), gate stage vmcnt counted
# speedup vs baseline: 1.0002x; 1.0002x over previous
.LBB0_224:
	global_atomic_add v3, v[144:145], v177, off sc0
	v_cvt_f32_u32_e32 v1, v2
	v_sub_u32_e32 v4, 0, v2
	v_rcp_iflag_f32_e32 v1, v1
	s_nop 0
	v_mul_f32_e32 v1, 0x4f7ffffe, v1
	v_cvt_u32_f32_e32 v1, v1
	v_mul_lo_u32 v4, v4, v1
	v_mul_hi_u32 v4, v1, v4
	v_add_u32_e32 v1, v1, v4
	s_waitcnt vmcnt(0)
	v_mul_hi_u32 v1, v3, v1
	v_mul_lo_u32 v4, v1, v2
	v_sub_u32_e32 v4, v3, v4
	v_add_u32_e32 v5, 1, v1
	v_cmp_ge_u32_e32 vcc, v4, v2
	v_add_u32_e32 v3, 1, v3
	s_nop 0
	v_cndmask_b32_e32 v1, v1, v5, vcc
	v_sub_u32_e32 v5, v4, v2
	v_cndmask_b32_e32 v4, v4, v5, vcc
	v_add_u32_e32 v5, 1, v1
	v_cmp_ge_u32_e32 vcc, v4, v2
	s_nop 1
	v_cndmask_b32_e32 v1, v1, v5, vcc
	v_mul_lo_u32 v4, v2, v1
	v_add_u32_e32 v2, v4, v2
	v_cmp_ne_u32_e32 vcc, v3, v2
	s_and_saveexec_b64 s[4:5], vcc
	s_xor_b64 s[4:5], exec, s[4:5]
	s_cbranch_execz .LBB0_238
	s_waitcnt lgkmcnt(0)
	v_readlane_b32 s100, v246, 24
	v_readlane_b32 s101, v246, 25
	s_nop 4
	global_load_dword v0, v149, s[100:101] sc1
	s_waitcnt vmcnt(0)
	v_cmp_eq_u32_e32 vcc, v0, v1
	s_and_saveexec_b64 s[8:9], vcc
	s_cbranch_execz .LBB0_237
	s_mov_b32 s1, 1
	s_mov_b64 s[10:11], 0
	s_branch .LBB0_228

.LBB0_230:
	global_load_dword v0, v149, s[100:101] sc1
	s_add_i32 s1, s1, 1
	s_mov_b64 s[22:23], -1
	s_waitcnt vmcnt(0)
	v_cmp_ne_u32_e32 vcc, v0, v1
	s_orn2_b64 s[20:21], vcc, exec
	s_branch .LBB0_227

.LBB0_328:
	global_atomic_add v3, v[144:145], v177, off sc0
	v_cvt_f32_u32_e32 v1, v2
	v_sub_u32_e32 v4, 0, v2
	v_rcp_iflag_f32_e32 v1, v1
	s_nop 0
	v_mul_f32_e32 v1, 0x4f7ffffe, v1
	v_cvt_u32_f32_e32 v1, v1
	v_mul_lo_u32 v4, v4, v1
	v_mul_hi_u32 v4, v1, v4
	v_add_u32_e32 v1, v1, v4
	s_waitcnt vmcnt(0)
	v_mul_hi_u32 v1, v3, v1
	v_mul_lo_u32 v4, v1, v2
	v_sub_u32_e32 v4, v3, v4
	v_add_u32_e32 v5, 1, v1
	v_cmp_ge_u32_e32 vcc, v4, v2
	v_add_u32_e32 v3, 1, v3
	s_nop 0
	v_cndmask_b32_e32 v1, v1, v5, vcc
	v_sub_u32_e32 v5, v4, v2
	v_cndmask_b32_e32 v4, v4, v5, vcc
	v_add_u32_e32 v5, 1, v1
	v_cmp_ge_u32_e32 vcc, v4, v2
	s_nop 1
	v_cndmask_b32_e32 v1, v1, v5, vcc
	v_mul_lo_u32 v4, v2, v1
	v_add_u32_e32 v2, v4, v2
	v_cmp_ne_u32_e32 vcc, v3, v2
	s_and_saveexec_b64 s[4:5], vcc
	s_xor_b64 s[4:5], exec, s[4:5]
	s_cbranch_execz .LBB0_342
	s_waitcnt lgkmcnt(0)
	v_readlane_b32 s100, v246, 24
	v_readlane_b32 s101, v246, 25
	s_nop 4
	global_load_dword v0, v149, s[100:101] sc1
	s_waitcnt vmcnt(0)
	v_cmp_eq_u32_e32 vcc, v0, v1
	s_and_saveexec_b64 s[8:9], vcc
	s_cbranch_execz .LBB0_341
	s_mov_b32 s36, 1
	s_mov_b64 s[10:11], 0
	s_branch .LBB0_332

.LBB0_334:
	global_load_dword v0, v149, s[100:101] sc1
	s_add_i32 s36, s36, 1
	s_mov_b64 s[22:23], -1
	s_waitcnt vmcnt(0)
	v_cmp_ne_u32_e32 vcc, v0, v1
	s_orn2_b64 s[20:21], vcc, exec
	s_branch .LBB0_331

.LBB0_526:
	global_atomic_add v3, v[144:145], v177, off sc0
	v_cvt_f32_u32_e32 v1, v2
	v_sub_u32_e32 v4, 0, v2
	v_rcp_iflag_f32_e32 v1, v1
	s_nop 0
	v_mul_f32_e32 v1, 0x4f7ffffe, v1
	v_cvt_u32_f32_e32 v1, v1
	v_mul_lo_u32 v4, v4, v1
	v_mul_hi_u32 v4, v1, v4
	v_add_u32_e32 v1, v1, v4
	s_waitcnt vmcnt(0)
	v_mul_hi_u32 v1, v3, v1
	v_mul_lo_u32 v4, v1, v2
	v_sub_u32_e32 v4, v3, v4
	v_add_u32_e32 v5, 1, v1
	v_cmp_ge_u32_e32 vcc, v4, v2
	v_add_u32_e32 v3, 1, v3
	s_nop 0
	v_cndmask_b32_e32 v1, v1, v5, vcc
	v_sub_u32_e32 v5, v4, v2
	v_cndmask_b32_e32 v4, v4, v5, vcc
	v_add_u32_e32 v5, 1, v1
	v_cmp_ge_u32_e32 vcc, v4, v2
	s_nop 1
	v_cndmask_b32_e32 v1, v1, v5, vcc
	v_mul_lo_u32 v4, v2, v1
	v_add_u32_e32 v2, v4, v2
	v_cmp_ne_u32_e32 vcc, v3, v2
	s_and_saveexec_b64 s[4:5], vcc
	s_xor_b64 s[4:5], exec, s[4:5]
	s_cbranch_execz .LBB0_540
	s_waitcnt lgkmcnt(0)
	v_readlane_b32 s100, v246, 24
	v_readlane_b32 s101, v246, 25
	s_nop 4
	global_load_dword v0, v149, s[100:101] sc1
	s_waitcnt vmcnt(0)
	v_cmp_eq_u32_e32 vcc, v0, v1
	s_and_saveexec_b64 s[8:9], vcc
	s_cbranch_execz .LBB0_539
	s_mov_b32 s3, 1
	s_mov_b64 s[20:21], 0
	s_branch .LBB0_530

.LBB0_532:
	global_load_dword v0, v149, s[100:101] sc1
	s_add_i32 s3, s3, 1
	s_mov_b64 s[42:43], -1
	s_waitcnt vmcnt(0)
	v_cmp_ne_u32_e32 vcc, v0, v1
	s_orn2_b64 s[40:41], vcc, exec
	s_branch .LBB0_529

.LBB0_667:
	global_load_dword v0, v149, s[100:101] sc1
	s_add_i32 s3, s3, 1
	s_mov_b64 s[40:41], -1
	s_waitcnt vmcnt(0)
	v_cmp_ne_u32_e32 vcc, v0, v1
	s_orn2_b64 s[38:39], vcc, exec
	s_branch .LBB0_664

.LBB0_731:
	global_atomic_add v3, v[144:145], v177, off sc0
	v_cvt_f32_u32_e32 v1, v2
	v_sub_u32_e32 v4, 0, v2
	v_rcp_iflag_f32_e32 v1, v1
	s_nop 0
	v_mul_f32_e32 v1, 0x4f7ffffe, v1
	v_cvt_u32_f32_e32 v1, v1
	v_mul_lo_u32 v4, v4, v1
	v_mul_hi_u32 v4, v1, v4
	v_add_u32_e32 v1, v1, v4
	s_waitcnt vmcnt(0)
	v_mul_hi_u32 v1, v3, v1
	v_mul_lo_u32 v4, v1, v2
	v_sub_u32_e32 v4, v3, v4
	v_add_u32_e32 v5, 1, v1
	v_cmp_ge_u32_e32 vcc, v4, v2
	v_add_u32_e32 v3, 1, v3
	s_nop 0
	v_cndmask_b32_e32 v1, v1, v5, vcc
	v_sub_u32_e32 v5, v4, v2
	v_cndmask_b32_e32 v4, v4, v5, vcc
	v_add_u32_e32 v5, 1, v1
	v_cmp_ge_u32_e32 vcc, v4, v2
	s_nop 1
	v_cndmask_b32_e32 v1, v1, v5, vcc
	v_mul_lo_u32 v4, v2, v1
	v_add_u32_e32 v2, v4, v2
	v_cmp_ne_u32_e32 vcc, v3, v2
	s_and_saveexec_b64 s[2:3], vcc
	s_xor_b64 s[2:3], exec, s[2:3]
	s_cbranch_execz .LBB0_745
	s_waitcnt lgkmcnt(0)
	v_readlane_b32 s100, v246, 24
	v_readlane_b32 s101, v246, 25
	s_nop 4
	global_load_dword v0, v149, s[100:101] sc1
	s_waitcnt vmcnt(0)
	v_cmp_eq_u32_e32 vcc, v0, v1
	s_and_saveexec_b64 s[4:5], vcc
	s_cbranch_execz .LBB0_744
	s_mov_b32 s24, 1
	s_mov_b64 s[8:9], 0
	s_branch .LBB0_735

.LBB0_737:
	global_load_dword v0, v149, s[100:101] sc1
	s_add_i32 s24, s24, 1
	s_mov_b64 s[20:21], -1
	s_waitcnt vmcnt(0)
	v_cmp_ne_u32_e32 vcc, v0, v1
	s_orn2_b64 s[14:15], vcc, exec
	s_branch .LBB0_734

	.amdhsa_kernel _Z4mega6Params
		.amdhsa_group_segment_fixed_size 0
		.amdhsa_private_segment_fixed_size 0
		.amdhsa_kernarg_size 408
		.amdhsa_user_sgpr_count 2
		.amdhsa_user_sgpr_dispatch_ptr 0
		.amdhsa_user_sgpr_queue_ptr 0
		.amdhsa_user_sgpr_kernarg_segment_ptr 1
		.amdhsa_user_sgpr_dispatch_id 0
		.amdhsa_user_sgpr_kernarg_preload_length 0
		.amdhsa_user_sgpr_kernarg_preload_offset 0
		.amdhsa_user_sgpr_private_segment_size 0
		.amdhsa_uses_dynamic_stack 0
		.amdhsa_enable_private_segment 0
		.amdhsa_system_sgpr_workgroup_id_x 1
		.amdhsa_system_sgpr_workgroup_id_y 0
		.amdhsa_system_sgpr_workgroup_id_z 0
		.amdhsa_system_sgpr_workgroup_info 0
		.amdhsa_system_vgpr_workitem_id 2
		.amdhsa_next_free_vgpr 248
		.amdhsa_next_free_sgpr 102
		.amdhsa_accum_offset 248
		.amdhsa_reserve_vcc 1
		.amdhsa_float_round_mode_32 0
		.amdhsa_float_round_mode_16_64 0
		.amdhsa_float_denorm_mode_32 3
		.amdhsa_float_denorm_mode_16_64 3
		.amdhsa_dx10_clamp 1
		.amdhsa_ieee_mode 1
		.amdhsa_fp16_overflow 0
		.amdhsa_tg_split 0
		.amdhsa_exception_fp_ieee_invalid_op 0
		.amdhsa_exception_fp_denorm_src 0
		.amdhsa_exception_fp_ieee_div_zero 0
		.amdhsa_exception_fp_ieee_overflow 0
		.amdhsa_exception_fp_ieee_underflow 0
		.amdhsa_exception_fp_ieee_inexact 0
		.amdhsa_exception_int_div_zero 0
	.end_amdhsa_kernel

amdhsa.kernels:
  - .agpr_count:     0
    .args:
      - .offset:         0
        .size:           152
        .value_kind:     by_value
      - .offset:         152
        .size:           4
        .value_kind:     hidden_block_count_x
      - .offset:         156
        .size:           4
        .value_kind:     hidden_block_count_y
      - .offset:         160
        .size:           4
        .value_kind:     hidden_block_count_z
      - .offset:         164
        .size:           2
        .value_kind:     hidden_group_size_x
      - .offset:         166
        .size:           2
        .value_kind:     hidden_group_size_y
      - .offset:         168
        .size:           2
        .value_kind:     hidden_group_size_z
      - .offset:         170
        .size:           2
        .value_kind:     hidden_remainder_x
      - .offset:         172
        .size:           2
        .value_kind:     hidden_remainder_y
      - .offset:         174
        .size:           2
        .value_kind:     hidden_remainder_z
      - .offset:         192
        .size:           8
        .value_kind:     hidden_global_offset_x
      - .offset:         200
        .size:           8
        .value_kind:     hidden_global_offset_y
      - .offset:         208
        .size:           8
        .value_kind:     hidden_global_offset_z
      - .offset:         216
        .size:           2
        .value_kind:     hidden_grid_dims
      - .offset:         240
        .size:           8
        .value_kind:     hidden_multigrid_sync_arg
      - .offset:         272
        .size:           4
        .value_kind:     hidden_dynamic_lds_size
    .group_segment_fixed_size: 0
    .kernarg_segment_align: 8
    .kernarg_segment_size: 408
    .language:       OpenCL C
    .language_version:
      - 2
      - 0
    .max_flat_workgroup_size: 512
    .name:           _Z4mega6Params
    .private_segment_fixed_size: 0
    .sgpr_count:     108
    .sgpr_spill_count: 229
    .symbol:         _Z4mega6Params.kd
    .uniform_work_group_size: 1
    .uses_dynamic_stack: false
    .vgpr_count:     248
    .vgpr_spill_count: 0
    .wavefront_size: 64
